# prologue: adaLN weight stream (50 MB, read once) loaded non-temporal (nt)
# speedup vs baseline: 1.0144x; 1.0144x over previous
.LBB0_1527:
	s_or_b64 exec, exec, s[12:13]
	s_ashr_i32 s2, s22, 6
	s_and_b32 s3, s22, 63
	s_waitcnt lgkmcnt(0)
	s_barrier
	s_and_saveexec_b64 s[12:13], s[4:5]
	s_cbranch_execz .LBB0_1529
	s_mov_b64 s[16:17], s[0:1]
	s_load_dwordx2 s[16:17], s[16:17], 0x58
	s_mul_i32 s20, s2, 0xc00000
	s_mul_hi_i32 s14, s2, 0xc00000
	s_mul_i32 s21, s3, 0xc0
	v_add_u32_e32 v119, 0x1000, v111
	s_waitcnt lgkmcnt(0)
	s_add_u32 s16, s16, s20
	s_addc_u32 s14, s17, s14
	s_add_u32 s16, s16, s21
	s_addc_u32 s17, s14, 0
	v_lshl_add_u64 v[94:95], v[24:25], 2, s[16:17]
	v_lshl_add_u64 v[0:1], v[94:95], 0, v[26:27]
	global_load_dwordx4 v[0:3], v[0:1], off nt
	v_lshl_add_u64 v[4:5], v[94:95], 0, v[28:29]
	global_load_dwordx4 v[16:19], v[4:5], off nt
	v_lshl_add_u64 v[4:5], v[94:95], 0, v[30:31]
	global_load_dwordx4 v[12:15], v[4:5], off nt
	v_lshl_add_u64 v[4:5], v[94:95], 0, v[32:33]
	global_load_dwordx4 v[20:23], v[4:5], off nt
	v_lshl_add_u64 v[4:5], v[94:95], 0, v[34:35]
	ds_read2_b32 v[96:97], v111 offset1:32
	ds_read2_b32 v[98:99], v119 offset1:32
	global_load_dwordx4 v[4:7], v[4:5], off nt
	v_add_u32_e32 v118, 0x2000, v111
	v_add_u32_e32 v117, 0x3000, v111
	v_add_u32_e32 v112, 0x4000, v111
	ds_read2_b32 v[100:101], v118 offset1:32
	ds_read2_b32 v[102:103], v117 offset1:32
	ds_read2_b32 v[104:105], v112 offset1:32
	v_lshl_add_u64 v[8:9], v[94:95], 0, v[36:37]
	global_load_dwordx4 v[8:11], v[8:9], off nt
	s_waitcnt vmcnt(5) lgkmcnt(4)
	v_pk_fma_f32 v[106:107], v[2:3], v[96:97], 0 op_sel_hi:[1,0,0]
	v_pk_fma_f32 v[108:109], v[0:1], v[96:97], 0 op_sel_hi:[1,0,0]
	s_waitcnt lgkmcnt(3)
	v_pk_fma_f32 v[122:123], v[0:1], v[98:99], 0 op_sel_hi:[1,0,0]
	s_waitcnt lgkmcnt(2)
	v_pk_fma_f32 v[126:127], v[0:1], v[100:101], 0 op_sel_hi:[1,0,0]
	s_waitcnt lgkmcnt(1)
	v_pk_fma_f32 v[130:131], v[0:1], v[102:103], 0 op_sel_hi:[1,0,0]
	s_waitcnt lgkmcnt(0)
	v_pk_fma_f32 v[134:135], v[0:1], v[104:105], 0 op_sel_hi:[1,0,0]
	v_mov_b32_e32 v0, v97
	v_pk_fma_f32 v[120:121], v[2:3], v[98:99], 0 op_sel_hi:[1,0,0]
	s_waitcnt vmcnt(4)
	v_pk_fma_f32 v[96:97], v[18:19], v[0:1], v[106:107] op_sel_hi:[1,0,1]
	v_pk_fma_f32 v[106:107], v[16:17], v[0:1], v[108:109] op_sel_hi:[1,0,1]
	v_mov_b32_e32 v0, v99
	v_pk_fma_f32 v[124:125], v[2:3], v[100:101], 0 op_sel_hi:[1,0,0]
	v_pk_fma_f32 v[98:99], v[18:19], v[0:1], v[120:121] op_sel_hi:[1,0,1]
	v_pk_fma_f32 v[120:121], v[16:17], v[0:1], v[122:123] op_sel_hi:[1,0,1]
	v_mov_b32_e32 v0, v101
	v_pk_fma_f32 v[128:129], v[2:3], v[102:103], 0 op_sel_hi:[1,0,0]
	v_pk_fma_f32 v[132:133], v[2:3], v[104:105], 0 op_sel_hi:[1,0,0]
	v_mov_b32_e32 v2, v103
	v_mov_b32_e32 v100, v105
	v_pk_fma_f32 v[102:103], v[18:19], v[0:1], v[124:125] op_sel_hi:[1,0,1]
	v_pk_fma_f32 v[104:105], v[16:17], v[0:1], v[126:127] op_sel_hi:[1,0,1]
	v_lshl_add_u64 v[0:1], v[94:95], 0, v[38:39]
	ds_read2_b32 v[108:109], v111 offset0:64 offset1:96
	ds_read2_b32 v[122:123], v119 offset0:64 offset1:96
	v_pk_fma_f32 v[124:125], v[18:19], v[2:3], v[128:129] op_sel_hi:[1,0,1]
	v_pk_fma_f32 v[126:127], v[16:17], v[2:3], v[130:131] op_sel_hi:[1,0,1]
	global_load_dwordx4 v[0:3], v[0:1], off nt
	v_pk_fma_f32 v[18:19], v[18:19], v[100:101], v[132:133] op_sel_hi:[1,0,1]
	v_pk_fma_f32 v[16:17], v[16:17], v[100:101], v[134:135] op_sel_hi:[1,0,1]
	ds_read2_b32 v[100:101], v118 offset0:64 offset1:96
	ds_read2_b32 v[128:129], v117 offset0:64 offset1:96
	ds_read2_b32 v[130:131], v112 offset0:64 offset1:96
	s_waitcnt vmcnt(4) lgkmcnt(4)
	v_pk_fma_f32 v[106:107], v[12:13], v[108:109], v[106:107] op_sel_hi:[1,0,1]
	s_waitcnt lgkmcnt(3)
	v_pk_fma_f32 v[120:121], v[12:13], v[122:123], v[120:121] op_sel_hi:[1,0,1]
	s_waitcnt lgkmcnt(2)
	v_pk_fma_f32 v[134:135], v[12:13], v[100:101], v[104:105] op_sel_hi:[1,0,1]
	s_waitcnt lgkmcnt(1)
	v_pk_fma_f32 v[126:127], v[12:13], v[128:129], v[126:127] op_sel_hi:[1,0,1]
	s_waitcnt lgkmcnt(0)
	v_pk_fma_f32 v[138:139], v[12:13], v[130:131], v[16:17] op_sel_hi:[1,0,1]
	v_lshl_add_u64 v[12:13], v[94:95], 0, v[40:41]
	v_pk_fma_f32 v[136:137], v[14:15], v[130:131], v[18:19] op_sel_hi:[1,0,1]
	global_load_dwordx4 v[16:19], v[12:13], off nt
	v_pk_fma_f32 v[96:97], v[14:15], v[108:109], v[96:97] op_sel_hi:[1,0,1]
	v_pk_fma_f32 v[98:99], v[14:15], v[122:123], v[98:99] op_sel_hi:[1,0,1]
	v_pk_fma_f32 v[132:133], v[14:15], v[100:101], v[102:103] op_sel_hi:[1,0,1]
	v_pk_fma_f32 v[124:125], v[14:15], v[128:129], v[124:125] op_sel_hi:[1,0,1]
	v_mov_b32_e32 v14, v123
	v_mov_b32_e32 v108, v101
	s_waitcnt vmcnt(4)
	v_pk_fma_f32 v[100:101], v[20:21], v[14:15], v[120:121] op_sel_hi:[1,0,1]
	v_mov_b32_e32 v120, v129
	v_mov_b32_e32 v12, v109
	v_pk_fma_f32 v[122:123], v[22:23], v[120:121], v[124:125] op_sel_hi:[1,0,1]
	v_pk_fma_f32 v[120:121], v[20:21], v[120:121], v[126:127] op_sel_hi:[1,0,1]
	v_mov_b32_e32 v126, v131
	v_pk_fma_f32 v[102:103], v[22:23], v[12:13], v[96:97] op_sel_hi:[1,0,1]
	v_pk_fma_f32 v[104:105], v[20:21], v[12:13], v[106:107] op_sel_hi:[1,0,1]
	v_pk_fma_f32 v[106:107], v[22:23], v[14:15], v[98:99] op_sel_hi:[1,0,1]
	v_pk_fma_f32 v[96:97], v[22:23], v[108:109], v[132:133] op_sel_hi:[1,0,1]
	v_pk_fma_f32 v[98:99], v[20:21], v[108:109], v[134:135] op_sel_hi:[1,0,1]
	ds_read2_b32 v[108:109], v111 offset0:128 offset1:160
	ds_read2_b32 v[124:125], v119 offset0:128 offset1:160
	v_pk_fma_f32 v[22:23], v[22:23], v[126:127], v[136:137] op_sel_hi:[1,0,1]
	v_pk_fma_f32 v[20:21], v[20:21], v[126:127], v[138:139] op_sel_hi:[1,0,1]
	ds_read2_b32 v[126:127], v118 offset0:128 offset1:160
	ds_read2_b32 v[128:129], v117 offset0:128 offset1:160
	ds_read2_b32 v[130:131], v112 offset0:128 offset1:160
	v_lshl_add_u64 v[12:13], v[94:95], 0, v[42:43]
	global_load_dwordx4 v[12:15], v[12:13], off nt
	s_waitcnt vmcnt(4) lgkmcnt(4)
	v_pk_fma_f32 v[104:105], v[4:5], v[108:109], v[104:105] op_sel_hi:[1,0,1]
	s_waitcnt lgkmcnt(3)
	v_pk_fma_f32 v[100:101], v[4:5], v[124:125], v[100:101] op_sel_hi:[1,0,1]
	s_waitcnt lgkmcnt(2)
	v_pk_fma_f32 v[98:99], v[4:5], v[126:127], v[98:99] op_sel_hi:[1,0,1]
	s_waitcnt lgkmcnt(1)
	v_pk_fma_f32 v[120:121], v[4:5], v[128:129], v[120:121] op_sel_hi:[1,0,1]
	s_waitcnt lgkmcnt(0)
	v_pk_fma_f32 v[4:5], v[4:5], v[130:131], v[20:21] op_sel_hi:[1,0,1]
	v_lshl_add_u64 v[20:21], v[94:95], 0, v[44:45]
	v_pk_fma_f32 v[102:103], v[6:7], v[108:109], v[102:103] op_sel_hi:[1,0,1]
	v_pk_fma_f32 v[106:107], v[6:7], v[124:125], v[106:107] op_sel_hi:[1,0,1]
	v_pk_fma_f32 v[96:97], v[6:7], v[126:127], v[96:97] op_sel_hi:[1,0,1]
	v_pk_fma_f32 v[122:123], v[6:7], v[128:129], v[122:123] op_sel_hi:[1,0,1]
	v_pk_fma_f32 v[6:7], v[6:7], v[130:131], v[22:23] op_sel_hi:[1,0,1]
	global_load_dwordx4 v[20:23], v[20:21], off nt
	v_mov_b32_e32 v126, v127
	v_mov_b32_e32 v108, v109
	s_waitcnt vmcnt(4)
	v_pk_fma_f32 v[96:97], v[10:11], v[126:127], v[96:97] op_sel_hi:[1,0,1]
	v_pk_fma_f32 v[98:99], v[8:9], v[126:127], v[98:99] op_sel_hi:[1,0,1]
	v_mov_b32_e32 v126, v129
	v_pk_fma_f32 v[102:103], v[10:11], v[108:109], v[102:103] op_sel_hi:[1,0,1]
	v_pk_fma_f32 v[104:105], v[8:9], v[108:109], v[104:105] op_sel_hi:[1,0,1]
	v_lshl_add_u64 v[108:109], v[94:95], 0, v[46:47]
	v_mov_b32_e32 v124, v125
	v_pk_fma_f32 v[122:123], v[10:11], v[126:127], v[122:123] op_sel_hi:[1,0,1]
	v_pk_fma_f32 v[120:121], v[8:9], v[126:127], v[120:121] op_sel_hi:[1,0,1]
	v_mov_b32_e32 v126, v131
	v_pk_fma_f32 v[106:107], v[10:11], v[124:125], v[106:107] op_sel_hi:[1,0,1]
	v_pk_fma_f32 v[100:101], v[8:9], v[124:125], v[100:101] op_sel_hi:[1,0,1]
	v_lshl_add_u64 v[124:125], v[94:95], 0, v[48:49]
	v_pk_fma_f32 v[128:129], v[10:11], v[126:127], v[6:7] op_sel_hi:[1,0,1]
	ds_read2_b32 v[130:131], v111 offset0:192 offset1:224
	v_pk_fma_f32 v[126:127], v[8:9], v[126:127], v[4:5] op_sel_hi:[1,0,1]
	ds_read2_b32 v[132:133], v119 offset0:192 offset1:224
	global_load_dwordx4 v[8:11], v[108:109], off nt
	global_load_dwordx4 v[4:7], v[124:125], off nt
	ds_read2_b32 v[108:109], v118 offset0:192 offset1:224
	ds_read2_b32 v[118:119], v117 offset0:192 offset1:224
	ds_read2_b32 v[124:125], v112 offset0:192 offset1:224
	s_waitcnt vmcnt(5) lgkmcnt(4)
	v_pk_fma_f32 v[102:103], v[2:3], v[130:131], v[102:103] op_sel_hi:[1,0,1]
	v_pk_fma_f32 v[104:105], v[0:1], v[130:131], v[104:105] op_sel_hi:[1,0,1]
	s_waitcnt lgkmcnt(2)
	v_pk_fma_f32 v[96:97], v[2:3], v[108:109], v[96:97] op_sel_hi:[1,0,1]
	v_pk_fma_f32 v[98:99], v[0:1], v[108:109], v[98:99] op_sel_hi:[1,0,1]
	v_mov_b32_e32 v108, v131
	v_pk_fma_f32 v[100:101], v[0:1], v[132:133], v[100:101] op_sel_hi:[1,0,1]
	v_pk_fma_f32 v[106:107], v[2:3], v[132:133], v[106:107] op_sel_hi:[1,0,1]
	s_waitcnt lgkmcnt(1)
	v_pk_fma_f32 v[122:123], v[2:3], v[118:119], v[122:123] op_sel_hi:[1,0,1]
	s_waitcnt lgkmcnt(0)
	v_pk_fma_f32 v[2:3], v[2:3], v[124:125], v[128:129] op_sel_hi:[1,0,1]
	v_pk_fma_f32 v[120:121], v[0:1], v[118:119], v[120:121] op_sel_hi:[1,0,1]
	v_pk_fma_f32 v[0:1], v[0:1], v[124:125], v[126:127] op_sel_hi:[1,0,1]
	s_waitcnt vmcnt(4)
	v_pk_fma_f32 v[102:103], v[18:19], v[108:109], v[102:103] op_sel_hi:[1,0,1]
	v_pk_fma_f32 v[104:105], v[16:17], v[108:109], v[104:105] op_sel_hi:[1,0,1]
	v_mov_b32_e32 v108, v133
	v_pk_fma_f32 v[128:129], v[16:17], v[108:109], v[100:101] op_sel_hi:[1,0,1]
	v_mov_b32_e32 v100, v109
	v_pk_fma_f32 v[106:107], v[18:19], v[108:109], v[106:107] op_sel_hi:[1,0,1]
	v_pk_fma_f32 v[108:109], v[18:19], v[100:101], v[96:97] op_sel_hi:[1,0,1]
	v_mov_b32_e32 v96, v119
	v_pk_fma_f32 v[118:119], v[18:19], v[96:97], v[122:123] op_sel_hi:[1,0,1]
	v_pk_fma_f32 v[120:121], v[16:17], v[96:97], v[120:121] op_sel_hi:[1,0,1]
	v_mov_b32_e32 v96, v125
	v_lshl_add_u64 v[126:127], v[94:95], 0, v[50:51]
	v_pk_fma_f32 v[130:131], v[16:17], v[100:101], v[98:99] op_sel_hi:[1,0,1]
	v_add_u32_e32 v99, 0x400, v111
	v_add_u32_e32 v100, 0x1400, v111
	v_pk_fma_f32 v[2:3], v[18:19], v[96:97], v[2:3] op_sel_hi:[1,0,1]
	v_pk_fma_f32 v[0:1], v[16:17], v[96:97], v[0:1] op_sel_hi:[1,0,1]
	v_add_u32_e32 v98, 0x2400, v111
	v_add_u32_e32 v97, 0x3400, v111
	v_add_u32_e32 v96, 0x4400, v111
	ds_read2_b32 v[122:123], v99 offset1:32
	ds_read2_b32 v[124:125], v100 offset1:32
	ds_read2_b32 v[132:133], v98 offset1:32
	ds_read2_b32 v[134:135], v97 offset1:32
	ds_read2_b32 v[136:137], v96 offset1:32
	global_load_dwordx4 v[16:19], v[126:127], off nt
	s_waitcnt vmcnt(4) lgkmcnt(4)
	v_pk_fma_f32 v[102:103], v[14:15], v[122:123], v[102:103] op_sel_hi:[1,0,1]
	v_pk_fma_f32 v[104:105], v[12:13], v[122:123], v[104:105] op_sel_hi:[1,0,1]
	s_waitcnt lgkmcnt(3)
	v_pk_fma_f32 v[106:107], v[14:15], v[124:125], v[106:107] op_sel_hi:[1,0,1]
	v_pk_fma_f32 v[128:129], v[12:13], v[124:125], v[128:129] op_sel_hi:[1,0,1]
	s_waitcnt lgkmcnt(2)
	v_pk_fma_f32 v[108:109], v[14:15], v[132:133], v[108:109] op_sel_hi:[1,0,1]
	v_pk_fma_f32 v[130:131], v[12:13], v[132:133], v[130:131] op_sel_hi:[1,0,1]
	s_waitcnt lgkmcnt(1)
	v_pk_fma_f32 v[118:119], v[14:15], v[134:135], v[118:119] op_sel_hi:[1,0,1]
	v_pk_fma_f32 v[120:121], v[12:13], v[134:135], v[120:121] op_sel_hi:[1,0,1]
	s_waitcnt lgkmcnt(0)
	v_pk_fma_f32 v[14:15], v[14:15], v[136:137], v[2:3] op_sel_hi:[1,0,1]
	v_pk_fma_f32 v[12:13], v[12:13], v[136:137], v[0:1] op_sel_hi:[1,0,1]
	v_lshl_add_u64 v[0:1], v[94:95], 0, v[52:53]
	v_mov_b32_e32 v2, v123
	s_waitcnt vmcnt(3)
	v_pk_fma_f32 v[102:103], v[22:23], v[2:3], v[102:103] op_sel_hi:[1,0,1]
	v_pk_fma_f32 v[104:105], v[20:21], v[2:3], v[104:105] op_sel_hi:[1,0,1]
	global_load_dwordx4 v[0:3], v[0:1], off nt
	v_mov_b32_e32 v112, v125
	v_pk_fma_f32 v[122:123], v[20:21], v[112:113], v[128:129] op_sel_hi:[1,0,1]
	ds_read2_b32 v[128:129], v99 offset0:64 offset1:96
	v_pk_fma_f32 v[106:107], v[22:23], v[112:113], v[106:107] op_sel_hi:[1,0,1]
	v_mov_b32_e32 v112, v133
	v_pk_fma_f32 v[108:109], v[22:23], v[112:113], v[108:109] op_sel_hi:[1,0,1]
	v_pk_fma_f32 v[126:127], v[20:21], v[112:113], v[130:131] op_sel_hi:[1,0,1]
	v_mov_b32_e32 v112, v135
	v_pk_fma_f32 v[118:119], v[22:23], v[112:113], v[118:119] op_sel_hi:[1,0,1]
	v_pk_fma_f32 v[120:121], v[20:21], v[112:113], v[120:121] op_sel_hi:[1,0,1]
	v_mov_b32_e32 v112, v137
	v_pk_fma_f32 v[14:15], v[22:23], v[112:113], v[14:15] op_sel_hi:[1,0,1]
	ds_read2_b32 v[22:23], v100 offset0:64 offset1:96
	v_pk_fma_f32 v[12:13], v[20:21], v[112:113], v[12:13] op_sel_hi:[1,0,1]
	ds_read2_b32 v[130:131], v97 offset0:64 offset1:96
	ds_read2_b32 v[132:133], v96 offset0:64 offset1:96
	s_waitcnt vmcnt(3) lgkmcnt(3)
	v_pk_fma_f32 v[20:21], v[10:11], v[128:129], v[102:103] op_sel_hi:[1,0,1]
	v_pk_fma_f32 v[102:103], v[8:9], v[128:129], v[104:105] op_sel_hi:[1,0,1]
	ds_read2_b32 v[104:105], v98 offset0:64 offset1:96
	v_lshl_add_u64 v[124:125], v[94:95], 0, v[54:55]
	s_waitcnt lgkmcnt(3)
	v_pk_fma_f32 v[106:107], v[10:11], v[22:23], v[106:107] op_sel_hi:[1,0,1]
	v_pk_fma_f32 v[122:123], v[8:9], v[22:23], v[122:123] op_sel_hi:[1,0,1]
	s_waitcnt lgkmcnt(2)
	v_pk_fma_f32 v[118:119], v[10:11], v[130:131], v[118:119] op_sel_hi:[1,0,1]
	s_waitcnt lgkmcnt(0)
	v_pk_fma_f32 v[108:109], v[10:11], v[104:105], v[108:109] op_sel_hi:[1,0,1]
	v_pk_fma_f32 v[126:127], v[8:9], v[104:105], v[126:127] op_sel_hi:[1,0,1]
	v_pk_fma_f32 v[120:121], v[8:9], v[130:131], v[120:121] op_sel_hi:[1,0,1]
	v_pk_fma_f32 v[134:135], v[10:11], v[132:133], v[14:15] op_sel_hi:[1,0,1]
	v_pk_fma_f32 v[136:137], v[8:9], v[132:133], v[12:13] op_sel_hi:[1,0,1]
	global_load_dwordx4 v[8:11], v[124:125], off nt
	v_lshl_add_u64 v[12:13], v[94:95], 0, v[56:57]
	v_mov_b32_e32 v14, v129
	v_mov_b32_e32 v112, v131
	s_waitcnt vmcnt(3)
	v_pk_fma_f32 v[20:21], v[6:7], v[14:15], v[20:21] op_sel_hi:[1,0,1]
	v_pk_fma_f32 v[102:103], v[4:5], v[14:15], v[102:103] op_sel_hi:[1,0,1]
	global_load_dwordx4 v[12:15], v[12:13], off nt
	v_pk_fma_f32 v[118:119], v[6:7], v[112:113], v[118:119] op_sel_hi:[1,0,1]
	v_pk_fma_f32 v[120:121], v[4:5], v[112:113], v[120:121] op_sel_hi:[1,0,1]
	v_mov_b32_e32 v112, v133
	ds_read2_b32 v[132:133], v96 offset0:128 offset1:160
	v_mov_b32_e32 v22, v23
	v_mov_b32_e32 v104, v105
	v_pk_fma_f32 v[106:107], v[6:7], v[22:23], v[106:107] op_sel_hi:[1,0,1]
	v_pk_fma_f32 v[22:23], v[4:5], v[22:23], v[122:123] op_sel_hi:[1,0,1]
	v_lshl_add_u64 v[122:123], v[94:95], 0, v[58:59]
	v_pk_fma_f32 v[108:109], v[6:7], v[104:105], v[108:109] op_sel_hi:[1,0,1]
	v_pk_fma_f32 v[104:105], v[4:5], v[104:105], v[126:127] op_sel_hi:[1,0,1]
	v_pk_fma_f32 v[6:7], v[6:7], v[112:113], v[134:135] op_sel_hi:[1,0,1]
	v_pk_fma_f32 v[4:5], v[4:5], v[112:113], v[136:137] op_sel_hi:[1,0,1]
	ds_read2_b32 v[126:127], v100 offset0:128 offset1:160
	ds_read2_b32 v[128:129], v98 offset0:128 offset1:160
	ds_read2_b32 v[130:131], v97 offset0:128 offset1:160
	ds_read2_b32 v[100:101], v100 offset0:192 offset1:224
	s_waitcnt vmcnt(3) lgkmcnt(4)
	v_pk_fma_f32 v[134:135], v[18:19], v[132:133], v[6:7] op_sel_hi:[1,0,1]
	v_pk_fma_f32 v[136:137], v[16:17], v[132:133], v[4:5] op_sel_hi:[1,0,1]
	global_load_dwordx4 v[4:7], v[122:123], off nt
	ds_read2_b32 v[124:125], v99 offset0:128 offset1:160
	s_waitcnt lgkmcnt(4)
	v_pk_fma_f32 v[106:107], v[18:19], v[126:127], v[106:107] op_sel_hi:[1,0,1]
	v_pk_fma_f32 v[22:23], v[16:17], v[126:127], v[22:23] op_sel_hi:[1,0,1]
	s_waitcnt lgkmcnt(3)
	v_pk_fma_f32 v[108:109], v[18:19], v[128:129], v[108:109] op_sel_hi:[1,0,1]
	v_pk_fma_f32 v[104:105], v[16:17], v[128:129], v[104:105] op_sel_hi:[1,0,1]
	s_waitcnt lgkmcnt(0)
	v_pk_fma_f32 v[20:21], v[18:19], v[124:125], v[20:21] op_sel_hi:[1,0,1]
	v_pk_fma_f32 v[102:103], v[16:17], v[124:125], v[102:103] op_sel_hi:[1,0,1]
	v_pk_fma_f32 v[118:119], v[18:19], v[130:131], v[118:119] op_sel_hi:[1,0,1]
	v_pk_fma_f32 v[120:121], v[16:17], v[130:131], v[120:121] op_sel_hi:[1,0,1]
	v_lshl_add_u64 v[16:17], v[94:95], 0, v[60:61]
	v_mov_b32_e32 v18, v125
	s_waitcnt vmcnt(3)
	v_pk_fma_f32 v[122:123], v[2:3], v[18:19], v[20:21] op_sel_hi:[1,0,1]
	v_pk_fma_f32 v[102:103], v[0:1], v[18:19], v[102:103] op_sel_hi:[1,0,1]
	global_load_dwordx4 v[16:19], v[16:17], off nt
	v_mov_b32_e32 v20, v127
	v_pk_fma_f32 v[124:125], v[0:1], v[20:21], v[22:23] op_sel_hi:[1,0,1]
	v_mov_b32_e32 v22, v129
	v_pk_fma_f32 v[108:109], v[2:3], v[22:23], v[108:109] op_sel_hi:[1,0,1]
	v_pk_fma_f32 v[104:105], v[0:1], v[22:23], v[104:105] op_sel_hi:[1,0,1]
	v_mov_b32_e32 v22, v131
	v_pk_fma_f32 v[106:107], v[2:3], v[20:21], v[106:107] op_sel_hi:[1,0,1]
	v_lshl_add_u64 v[20:21], v[94:95], 0, v[62:63]
	v_pk_fma_f32 v[118:119], v[2:3], v[22:23], v[118:119] op_sel_hi:[1,0,1]
	v_pk_fma_f32 v[120:121], v[0:1], v[22:23], v[120:121] op_sel_hi:[1,0,1]
	v_mov_b32_e32 v22, v133
	v_lshl_add_u64 v[126:127], v[94:95], 0, v[64:65]
	v_pk_fma_f32 v[128:129], v[2:3], v[22:23], v[134:135] op_sel_hi:[1,0,1]
	ds_read2_b32 v[130:131], v99 offset0:192 offset1:224
	v_pk_fma_f32 v[132:133], v[0:1], v[22:23], v[136:137] op_sel_hi:[1,0,1]
	global_load_dwordx4 v[20:23], v[20:21], off nt
	s_nop 0
	global_load_dwordx4 v[0:3], v[126:127], off nt
	ds_read2_b32 v[98:99], v98 offset0:192 offset1:224
	ds_read2_b32 v[126:127], v97 offset0:192 offset1:224
	ds_read2_b32 v[96:97], v96 offset0:192 offset1:224
	s_waitcnt vmcnt(5) lgkmcnt(3)
	v_pk_fma_f32 v[122:123], v[10:11], v[130:131], v[122:123] op_sel_hi:[1,0,1]
	v_pk_fma_f32 v[102:103], v[8:9], v[130:131], v[102:103] op_sel_hi:[1,0,1]
	v_pk_fma_f32 v[106:107], v[10:11], v[100:101], v[106:107] op_sel_hi:[1,0,1]
	v_pk_fma_f32 v[124:125], v[8:9], v[100:101], v[124:125] op_sel_hi:[1,0,1]
	s_waitcnt lgkmcnt(2)
	v_pk_fma_f32 v[108:109], v[10:11], v[98:99], v[108:109] op_sel_hi:[1,0,1]
	v_pk_fma_f32 v[104:105], v[8:9], v[98:99], v[104:105] op_sel_hi:[1,0,1]
	s_waitcnt lgkmcnt(1)
	v_pk_fma_f32 v[118:119], v[10:11], v[126:127], v[118:119] op_sel_hi:[1,0,1]
	v_pk_fma_f32 v[120:121], v[8:9], v[126:127], v[120:121] op_sel_hi:[1,0,1]
	s_waitcnt lgkmcnt(0)
	v_pk_fma_f32 v[10:11], v[10:11], v[96:97], v[128:129] op_sel_hi:[1,0,1]
	v_pk_fma_f32 v[8:9], v[8:9], v[96:97], v[132:133] op_sel_hi:[1,0,1]
	v_mov_b32_e32 v96, v131
	s_waitcnt vmcnt(4)
	v_pk_fma_f32 v[122:123], v[14:15], v[96:97], v[122:123] op_sel_hi:[1,0,1]
	v_pk_fma_f32 v[102:103], v[12:13], v[96:97], v[102:103] op_sel_hi:[1,0,1]
	v_mov_b32_e32 v96, v101
	v_pk_fma_f32 v[106:107], v[14:15], v[96:97], v[106:107] op_sel_hi:[1,0,1]
	v_pk_fma_f32 v[124:125], v[12:13], v[96:97], v[124:125] op_sel_hi:[1,0,1]
	v_mov_b32_e32 v96, v99
	v_pk_fma_f32 v[108:109], v[14:15], v[96:97], v[108:109] op_sel_hi:[1,0,1]
	v_pk_fma_f32 v[104:105], v[12:13], v[96:97], v[104:105] op_sel_hi:[1,0,1]
	v_mov_b32_e32 v96, v127
	v_pk_fma_f32 v[118:119], v[14:15], v[96:97], v[118:119] op_sel_hi:[1,0,1]
	v_pk_fma_f32 v[120:121], v[12:13], v[96:97], v[120:121] op_sel_hi:[1,0,1]
	v_mov_b32_e32 v96, v97
	v_lshl_add_u64 v[128:129], v[94:95], 0, v[66:67]
	v_add_u32_e32 v100, 0x800, v111
	v_add_u32_e32 v99, 0x1800, v111
	v_pk_fma_f32 v[10:11], v[14:15], v[96:97], v[10:11] op_sel_hi:[1,0,1]
	v_pk_fma_f32 v[8:9], v[12:13], v[96:97], v[8:9] op_sel_hi:[1,0,1]
	v_add_u32_e32 v98, 0x2800, v111
	v_add_u32_e32 v97, 0x3800, v111
	v_add_u32_e32 v96, 0x4800, v111
	ds_read2_b32 v[126:127], v100 offset1:32
	ds_read2_b32 v[130:131], v99 offset1:32
	ds_read2_b32 v[132:133], v98 offset1:32
	ds_read2_b32 v[134:135], v97 offset1:32
	ds_read2_b32 v[136:137], v96 offset1:32
	global_load_dwordx4 v[12:15], v[128:129], off nt
	ds_read2_b32 v[128:129], v100 offset0:64 offset1:96
	s_waitcnt vmcnt(4) lgkmcnt(5)
	v_pk_fma_f32 v[122:123], v[6:7], v[126:127], v[122:123] op_sel_hi:[1,0,1]
	v_pk_fma_f32 v[102:103], v[4:5], v[126:127], v[102:103] op_sel_hi:[1,0,1]
	s_waitcnt lgkmcnt(4)
	v_pk_fma_f32 v[106:107], v[6:7], v[130:131], v[106:107] op_sel_hi:[1,0,1]
	v_pk_fma_f32 v[124:125], v[4:5], v[130:131], v[124:125] op_sel_hi:[1,0,1]
	s_waitcnt lgkmcnt(3)
	v_pk_fma_f32 v[108:109], v[6:7], v[132:133], v[108:109] op_sel_hi:[1,0,1]
	v_pk_fma_f32 v[104:105], v[4:5], v[132:133], v[104:105] op_sel_hi:[1,0,1]
	s_waitcnt lgkmcnt(2)
	v_pk_fma_f32 v[118:119], v[6:7], v[134:135], v[118:119] op_sel_hi:[1,0,1]
	v_pk_fma_f32 v[120:121], v[4:5], v[134:135], v[120:121] op_sel_hi:[1,0,1]
	s_waitcnt lgkmcnt(1)
	v_pk_fma_f32 v[10:11], v[6:7], v[136:137], v[10:11] op_sel_hi:[1,0,1]
	v_pk_fma_f32 v[8:9], v[4:5], v[136:137], v[8:9] op_sel_hi:[1,0,1]
	v_lshl_add_u64 v[4:5], v[94:95], 0, v[68:69]
	v_mov_b32_e32 v6, v127
	v_mov_b32_e32 v112, v131
	ds_read2_b32 v[130:131], v99 offset0:64 offset1:96
	v_lshl_add_u64 v[126:127], v[94:95], 0, v[70:71]
	s_waitcnt vmcnt(3)
	v_pk_fma_f32 v[122:123], v[18:19], v[6:7], v[122:123] op_sel_hi:[1,0,1]
	v_pk_fma_f32 v[102:103], v[16:17], v[6:7], v[102:103] op_sel_hi:[1,0,1]
	global_load_dwordx4 v[4:7], v[4:5], off nt
	v_pk_fma_f32 v[106:107], v[18:19], v[112:113], v[106:107] op_sel_hi:[1,0,1]
	v_pk_fma_f32 v[124:125], v[16:17], v[112:113], v[124:125] op_sel_hi:[1,0,1]
	v_mov_b32_e32 v112, v133
	v_pk_fma_f32 v[108:109], v[18:19], v[112:113], v[108:109] op_sel_hi:[1,0,1]
	v_pk_fma_f32 v[104:105], v[16:17], v[112:113], v[104:105] op_sel_hi:[1,0,1]
	v_mov_b32_e32 v112, v135
	v_pk_fma_f32 v[118:119], v[18:19], v[112:113], v[118:119] op_sel_hi:[1,0,1]
	v_pk_fma_f32 v[120:121], v[16:17], v[112:113], v[120:121] op_sel_hi:[1,0,1]
	v_mov_b32_e32 v112, v137
	v_pk_fma_f32 v[10:11], v[18:19], v[112:113], v[10:11] op_sel_hi:[1,0,1]
	v_pk_fma_f32 v[8:9], v[16:17], v[112:113], v[8:9] op_sel_hi:[1,0,1]
	ds_read2_b32 v[132:133], v96 offset0:64 offset1:96
	s_waitcnt vmcnt(3) lgkmcnt(2)
	v_pk_fma_f32 v[18:19], v[20:21], v[128:129], v[102:103] op_sel_hi:[1,0,1]
	ds_read2_b32 v[102:103], v98 offset0:64 offset1:96
	v_pk_fma_f32 v[16:17], v[22:23], v[128:129], v[122:123] op_sel_hi:[1,0,1]
	ds_read2_b32 v[122:123], v97 offset0:64 offset1:96
	s_waitcnt lgkmcnt(3)
	v_pk_fma_f32 v[106:107], v[22:23], v[130:131], v[106:107] op_sel_hi:[1,0,1]
	v_pk_fma_f32 v[124:125], v[20:21], v[130:131], v[124:125] op_sel_hi:[1,0,1]
	s_waitcnt lgkmcnt(1)
	v_pk_fma_f32 v[108:109], v[22:23], v[102:103], v[108:109] op_sel_hi:[1,0,1]
	v_pk_fma_f32 v[104:105], v[20:21], v[102:103], v[104:105] op_sel_hi:[1,0,1]
	v_mov_b32_e32 v102, v129
	s_waitcnt vmcnt(2)
	v_pk_fma_f32 v[128:129], v[2:3], v[102:103], v[16:17] op_sel_hi:[1,0,1]
	v_pk_fma_f32 v[134:135], v[0:1], v[102:103], v[18:19] op_sel_hi:[1,0,1]
	v_mov_b32_e32 v102, v131
	v_pk_fma_f32 v[106:107], v[2:3], v[102:103], v[106:107] op_sel_hi:[1,0,1]
	v_pk_fma_f32 v[124:125], v[0:1], v[102:103], v[124:125] op_sel_hi:[1,0,1]
	v_mov_b32_e32 v102, v103
	s_waitcnt lgkmcnt(0)
	v_pk_fma_f32 v[118:119], v[22:23], v[122:123], v[118:119] op_sel_hi:[1,0,1]
	v_pk_fma_f32 v[120:121], v[20:21], v[122:123], v[120:121] op_sel_hi:[1,0,1]
	v_pk_fma_f32 v[108:109], v[2:3], v[102:103], v[108:109] op_sel_hi:[1,0,1]
	v_pk_fma_f32 v[102:103], v[0:1], v[102:103], v[104:105] op_sel_hi:[1,0,1]
	v_mov_b32_e32 v104, v123
	v_pk_fma_f32 v[118:119], v[2:3], v[104:105], v[118:119] op_sel_hi:[1,0,1]
	v_pk_fma_f32 v[104:105], v[0:1], v[104:105], v[120:121] op_sel_hi:[1,0,1]
	ds_read2_b32 v[120:121], v100 offset0:128 offset1:160
	v_pk_fma_f32 v[22:23], v[22:23], v[132:133], v[10:11] op_sel_hi:[1,0,1]
	v_pk_fma_f32 v[20:21], v[20:21], v[132:133], v[8:9] op_sel_hi:[1,0,1]
	global_load_dwordx4 v[8:11], v[126:127], off nt
	v_lshl_add_u64 v[126:127], v[94:95], 0, v[72:73]
	global_load_dwordx4 v[16:19], v[126:127], off nt
	v_mov_b32_e32 v112, v133
	v_pk_fma_f32 v[2:3], v[2:3], v[112:113], v[22:23] op_sel_hi:[1,0,1]
	ds_read2_b32 v[22:23], v99 offset0:128 offset1:160
	v_pk_fma_f32 v[0:1], v[0:1], v[112:113], v[20:21] op_sel_hi:[1,0,1]
	ds_read2_b32 v[130:131], v97 offset0:128 offset1:160
	ds_read2_b32 v[132:133], v96 offset0:128 offset1:160
	v_lshl_add_u64 v[126:127], v[94:95], 0, v[78:79]
	ds_read2_b32 v[100:101], v100 offset0:192 offset1:224
	s_waitcnt lgkmcnt(2)
	v_mov_b32_e32 v112, v131
	s_waitcnt vmcnt(3)
	v_pk_fma_f32 v[20:21], v[14:15], v[120:121], v[128:129] op_sel_hi:[1,0,1]
	ds_read2_b32 v[128:129], v98 offset0:128 offset1:160
	v_pk_fma_f32 v[122:123], v[12:13], v[120:121], v[134:135] op_sel_hi:[1,0,1]
	v_pk_fma_f32 v[106:107], v[14:15], v[22:23], v[106:107] op_sel_hi:[1,0,1]
	v_pk_fma_f32 v[124:125], v[12:13], v[22:23], v[124:125] op_sel_hi:[1,0,1]
	v_pk_fma_f32 v[118:119], v[14:15], v[130:131], v[118:119] op_sel_hi:[1,0,1]
	s_waitcnt lgkmcnt(0)
	v_pk_fma_f32 v[108:109], v[14:15], v[128:129], v[108:109] op_sel_hi:[1,0,1]
	v_pk_fma_f32 v[134:135], v[12:13], v[128:129], v[102:103] op_sel_hi:[1,0,1]
	v_pk_fma_f32 v[136:137], v[12:13], v[130:131], v[104:105] op_sel_hi:[1,0,1]
	v_pk_fma_f32 v[2:3], v[14:15], v[132:133], v[2:3] op_sel_hi:[1,0,1]
	v_pk_fma_f32 v[0:1], v[12:13], v[132:133], v[0:1] op_sel_hi:[1,0,1]
	global_load_dwordx4 v[102:105], v[126:127], off nt
	v_lshl_add_u64 v[12:13], v[94:95], 0, v[80:81]
	v_mov_b32_e32 v14, v121
	v_mov_b32_e32 v22, v129
	v_lshl_add_u64 v[130:131], v[94:95], 0, v[84:85]
	s_waitcnt vmcnt(3)
	v_pk_fma_f32 v[120:121], v[6:7], v[14:15], v[20:21] op_sel_hi:[1,0,1]
	v_pk_fma_f32 v[122:123], v[4:5], v[14:15], v[122:123] op_sel_hi:[1,0,1]
	global_load_dwordx4 v[12:15], v[12:13], off nt
	v_mov_b32_e32 v20, v23
	v_pk_fma_f32 v[106:107], v[6:7], v[20:21], v[106:107] op_sel_hi:[1,0,1]
	v_pk_fma_f32 v[124:125], v[4:5], v[20:21], v[124:125] op_sel_hi:[1,0,1]
	v_lshl_add_u64 v[20:21], v[94:95], 0, v[82:83]
	v_pk_fma_f32 v[108:109], v[6:7], v[22:23], v[108:109] op_sel_hi:[1,0,1]
	v_pk_fma_f32 v[126:127], v[4:5], v[22:23], v[134:135] op_sel_hi:[1,0,1]
	global_load_dwordx4 v[20:23], v[20:21], off nt
	v_pk_fma_f32 v[118:119], v[6:7], v[112:113], v[118:119] op_sel_hi:[1,0,1]
	v_pk_fma_f32 v[128:129], v[4:5], v[112:113], v[136:137] op_sel_hi:[1,0,1]
	v_mov_b32_e32 v112, v133
	v_pk_fma_f32 v[6:7], v[6:7], v[112:113], v[2:3] op_sel_hi:[1,0,1]
	v_pk_fma_f32 v[4:5], v[4:5], v[112:113], v[0:1] op_sel_hi:[1,0,1]
	ds_read2_b32 v[132:133], v99 offset0:192 offset1:224
	global_load_dwordx4 v[0:3], v[130:131], off nt
	ds_read2_b32 v[98:99], v98 offset0:192 offset1:224
	ds_read2_b32 v[130:131], v97 offset0:192 offset1:224
	ds_read2_b32 v[96:97], v96 offset0:192 offset1:224
	v_lshl_add_u64 v[134:135], v[94:95], 0, v[88:89]
	s_waitcnt lgkmcnt(0)
	v_mov_b32_e32 v112, v97
	s_waitcnt vmcnt(5)
	v_pk_fma_f32 v[120:121], v[10:11], v[100:101], v[120:121] op_sel_hi:[1,0,1]
	v_pk_fma_f32 v[106:107], v[10:11], v[132:133], v[106:107] op_sel_hi:[1,0,1]
	v_pk_fma_f32 v[124:125], v[8:9], v[132:133], v[124:125] op_sel_hi:[1,0,1]
	v_pk_fma_f32 v[108:109], v[10:11], v[98:99], v[108:109] op_sel_hi:[1,0,1]
	v_pk_fma_f32 v[118:119], v[10:11], v[130:131], v[118:119] op_sel_hi:[1,0,1]
	v_pk_fma_f32 v[6:7], v[10:11], v[96:97], v[6:7] op_sel_hi:[1,0,1]
	v_pk_fma_f32 v[4:5], v[8:9], v[96:97], v[4:5] op_sel_hi:[1,0,1]
	v_mov_b32_e32 v10, v101
	v_mov_b32_e32 v96, v133
	v_pk_fma_f32 v[122:123], v[8:9], v[100:101], v[122:123] op_sel_hi:[1,0,1]
	v_pk_fma_f32 v[126:127], v[8:9], v[98:99], v[126:127] op_sel_hi:[1,0,1]
	s_waitcnt vmcnt(4)
	v_pk_fma_f32 v[100:101], v[18:19], v[10:11], v[120:121] op_sel_hi:[1,0,1]
	v_pk_fma_f32 v[106:107], v[18:19], v[96:97], v[106:107] op_sel_hi:[1,0,1]
	v_pk_fma_f32 v[120:121], v[16:17], v[96:97], v[124:125] op_sel_hi:[1,0,1]
	v_mov_b32_e32 v96, v99
	v_pk_fma_f32 v[128:129], v[8:9], v[130:131], v[128:129] op_sel_hi:[1,0,1]
	v_pk_fma_f32 v[98:99], v[18:19], v[96:97], v[108:109] op_sel_hi:[1,0,1]
	v_pk_fma_f32 v[108:109], v[16:17], v[96:97], v[126:127] op_sel_hi:[1,0,1]
	v_mov_b32_e32 v96, v131
	v_pk_fma_f32 v[10:11], v[16:17], v[10:11], v[122:123] op_sel_hi:[1,0,1]
	v_pk_fma_f32 v[118:119], v[18:19], v[96:97], v[118:119] op_sel_hi:[1,0,1]
	v_pk_fma_f32 v[122:123], v[16:17], v[96:97], v[128:129] op_sel_hi:[1,0,1]
	v_add_u32_e32 v97, 0xc00, v111
	v_add_u32_e32 v96, 0x1c00, v111
	v_pk_fma_f32 v[6:7], v[18:19], v[112:113], v[6:7] op_sel_hi:[1,0,1]
	v_pk_fma_f32 v[4:5], v[16:17], v[112:113], v[4:5] op_sel_hi:[1,0,1]
	v_add_u32_e32 v18, 0x2c00, v111
	v_add_u32_e32 v17, 0x3c00, v111
	v_add_u32_e32 v16, 0x4c00, v111
	ds_read2_b32 v[124:125], v97 offset1:32
	ds_read2_b32 v[126:127], v96 offset1:32
	ds_read2_b32 v[128:129], v18 offset1:32
	ds_read2_b32 v[130:131], v17 offset1:32
	ds_read2_b32 v[132:133], v16 offset1:32
	v_lshl_add_u64 v[8:9], v[94:95], 0, v[86:87]
	s_waitcnt vmcnt(3) lgkmcnt(4)
	v_pk_fma_f32 v[100:101], v[104:105], v[124:125], v[100:101] op_sel_hi:[1,0,1]
	v_pk_fma_f32 v[10:11], v[102:103], v[124:125], v[10:11] op_sel_hi:[1,0,1]
	s_waitcnt lgkmcnt(3)
	v_pk_fma_f32 v[106:107], v[104:105], v[126:127], v[106:107] op_sel_hi:[1,0,1]
	v_pk_fma_f32 v[120:121], v[102:103], v[126:127], v[120:121] op_sel_hi:[1,0,1]
	s_waitcnt lgkmcnt(2)
	v_pk_fma_f32 v[108:109], v[102:103], v[128:129], v[108:109] op_sel_hi:[1,0,1]
	s_waitcnt lgkmcnt(1)
	v_pk_fma_f32 v[122:123], v[102:103], v[130:131], v[122:123] op_sel_hi:[1,0,1]
	s_waitcnt lgkmcnt(0)
	v_pk_fma_f32 v[102:103], v[102:103], v[132:133], v[4:5] op_sel_hi:[1,0,1]
	v_mov_b32_e32 v4, v125
	v_mov_b32_e32 v112, v127
	v_pk_fma_f32 v[98:99], v[104:105], v[128:129], v[98:99] op_sel_hi:[1,0,1]
	v_pk_fma_f32 v[118:119], v[104:105], v[130:131], v[118:119] op_sel_hi:[1,0,1]
	v_pk_fma_f32 v[104:105], v[104:105], v[132:133], v[6:7] op_sel_hi:[1,0,1]
	s_waitcnt vmcnt(2)
	v_pk_fma_f32 v[100:101], v[14:15], v[4:5], v[100:101] op_sel_hi:[1,0,1]
	v_pk_fma_f32 v[124:125], v[12:13], v[4:5], v[10:11] op_sel_hi:[1,0,1]
	global_load_dwordx4 v[4:7], v[8:9], off nt
	s_nop 0
	global_load_dwordx4 v[8:11], v[134:135], off nt
	v_pk_fma_f32 v[106:107], v[14:15], v[112:113], v[106:107] op_sel_hi:[1,0,1]
	v_pk_fma_f32 v[120:121], v[12:13], v[112:113], v[120:121] op_sel_hi:[1,0,1]
	v_mov_b32_e32 v112, v129
	ds_read2_b32 v[128:129], v97 offset0:64 offset1:96
	v_pk_fma_f32 v[98:99], v[14:15], v[112:113], v[98:99] op_sel_hi:[1,0,1]
	v_pk_fma_f32 v[108:109], v[12:13], v[112:113], v[108:109] op_sel_hi:[1,0,1]
	v_mov_b32_e32 v112, v131
	v_pk_fma_f32 v[118:119], v[14:15], v[112:113], v[118:119] op_sel_hi:[1,0,1]
	v_pk_fma_f32 v[122:123], v[12:13], v[112:113], v[122:123] op_sel_hi:[1,0,1]
	v_mov_b32_e32 v112, v133
	v_pk_fma_f32 v[14:15], v[14:15], v[112:113], v[104:105] op_sel_hi:[1,0,1]
	ds_read2_b32 v[104:105], v96 offset0:64 offset1:96
	v_pk_fma_f32 v[12:13], v[12:13], v[112:113], v[102:103] op_sel_hi:[1,0,1]
	s_waitcnt vmcnt(3) lgkmcnt(1)
	v_pk_fma_f32 v[102:103], v[20:21], v[128:129], v[124:125] op_sel_hi:[1,0,1]
	ds_read2_b32 v[124:125], v18 offset0:64 offset1:96
	ds_read2_b32 v[130:131], v17 offset0:64 offset1:96
	ds_read2_b32 v[132:133], v16 offset0:64 offset1:96
	v_lshl_add_u64 v[126:127], v[94:95], 0, v[90:91]
	s_waitcnt lgkmcnt(3)
	v_pk_fma_f32 v[120:121], v[20:21], v[104:105], v[120:121] op_sel_hi:[1,0,1]
	s_waitcnt lgkmcnt(2)
	v_pk_fma_f32 v[108:109], v[20:21], v[124:125], v[108:109] op_sel_hi:[1,0,1]
	s_waitcnt lgkmcnt(1)
	v_pk_fma_f32 v[122:123], v[20:21], v[130:131], v[122:123] op_sel_hi:[1,0,1]
	s_waitcnt lgkmcnt(0)
	v_pk_fma_f32 v[134:135], v[22:23], v[132:133], v[14:15] op_sel_hi:[1,0,1]
	v_pk_fma_f32 v[136:137], v[20:21], v[132:133], v[12:13] op_sel_hi:[1,0,1]
	global_load_dwordx4 v[12:15], v[126:127], off nt
	v_lshl_add_u64 v[20:21], v[94:95], 0, v[92:93]
	v_pk_fma_f32 v[100:101], v[22:23], v[128:129], v[100:101] op_sel_hi:[1,0,1]
	v_pk_fma_f32 v[106:107], v[22:23], v[104:105], v[106:107] op_sel_hi:[1,0,1]
	v_pk_fma_f32 v[98:99], v[22:23], v[124:125], v[98:99] op_sel_hi:[1,0,1]
	v_pk_fma_f32 v[118:119], v[22:23], v[130:131], v[118:119] op_sel_hi:[1,0,1]
	global_load_dwordx4 v[20:23], v[20:21], off nt
	v_mov_b32_e32 v94, v129
	s_waitcnt vmcnt(4)
	v_pk_fma_f32 v[100:101], v[2:3], v[94:95], v[100:101] op_sel_hi:[1,0,1]
	v_pk_fma_f32 v[94:95], v[0:1], v[94:95], v[102:103] op_sel_hi:[1,0,1]
	v_mov_b32_e32 v102, v105
	v_pk_fma_f32 v[104:105], v[2:3], v[102:103], v[106:107] op_sel_hi:[1,0,1]
	v_mov_b32_e32 v106, v125
	v_pk_fma_f32 v[98:99], v[2:3], v[106:107], v[98:99] op_sel_hi:[1,0,1]
	v_pk_fma_f32 v[106:107], v[0:1], v[106:107], v[108:109] op_sel_hi:[1,0,1]
	v_mov_b32_e32 v108, v131
	v_pk_fma_f32 v[102:103], v[0:1], v[102:103], v[120:121] op_sel_hi:[1,0,1]
	v_pk_fma_f32 v[118:119], v[2:3], v[108:109], v[118:119] op_sel_hi:[1,0,1]
	v_pk_fma_f32 v[108:109], v[0:1], v[108:109], v[122:123] op_sel_hi:[1,0,1]
	ds_read2_b32 v[120:121], v97 offset0:128 offset1:160
	ds_read2_b32 v[122:123], v96 offset0:128 offset1:160
	ds_read2_b32 v[124:125], v18 offset0:128 offset1:160
	ds_read2_b32 v[126:127], v17 offset0:128 offset1:160
	ds_read2_b32 v[128:129], v16 offset0:128 offset1:160
	v_mov_b32_e32 v112, v133
	v_pk_fma_f32 v[0:1], v[0:1], v[112:113], v[136:137] op_sel_hi:[1,0,1]
	v_pk_fma_f32 v[2:3], v[2:3], v[112:113], v[134:135] op_sel_hi:[1,0,1]
	s_waitcnt lgkmcnt(0)
	v_mov_b32_e32 v112, v129
	s_waitcnt vmcnt(3)
	v_pk_fma_f32 v[100:101], v[6:7], v[120:121], v[100:101] op_sel_hi:[1,0,1]
	v_pk_fma_f32 v[94:95], v[4:5], v[120:121], v[94:95] op_sel_hi:[1,0,1]
	v_pk_fma_f32 v[102:103], v[4:5], v[122:123], v[102:103] op_sel_hi:[1,0,1]
	v_pk_fma_f32 v[106:107], v[4:5], v[124:125], v[106:107] op_sel_hi:[1,0,1]
	v_pk_fma_f32 v[108:109], v[4:5], v[126:127], v[108:109] op_sel_hi:[1,0,1]
	v_pk_fma_f32 v[0:1], v[4:5], v[128:129], v[0:1] op_sel_hi:[1,0,1]
	v_mov_b32_e32 v4, v121
	v_pk_fma_f32 v[104:105], v[6:7], v[122:123], v[104:105] op_sel_hi:[1,0,1]
	v_pk_fma_f32 v[98:99], v[6:7], v[124:125], v[98:99] op_sel_hi:[1,0,1]
	v_pk_fma_f32 v[118:119], v[6:7], v[126:127], v[118:119] op_sel_hi:[1,0,1]
	v_pk_fma_f32 v[2:3], v[6:7], v[128:129], v[2:3] op_sel_hi:[1,0,1]
	s_waitcnt vmcnt(2)
	v_pk_fma_f32 v[6:7], v[10:11], v[4:5], v[100:101] op_sel_hi:[1,0,1]
	v_pk_fma_f32 v[4:5], v[8:9], v[4:5], v[94:95] op_sel_hi:[1,0,1]
	v_mov_b32_e32 v94, v123
	v_pk_fma_f32 v[100:101], v[10:11], v[94:95], v[104:105] op_sel_hi:[1,0,1]
	v_pk_fma_f32 v[94:95], v[8:9], v[94:95], v[102:103] op_sel_hi:[1,0,1]
	v_mov_b32_e32 v102, v125
	v_mov_b32_e32 v104, v127
	v_pk_fma_f32 v[98:99], v[10:11], v[102:103], v[98:99] op_sel_hi:[1,0,1]
	v_pk_fma_f32 v[102:103], v[8:9], v[102:103], v[106:107] op_sel_hi:[1,0,1]
	v_pk_fma_f32 v[106:107], v[10:11], v[104:105], v[118:119] op_sel_hi:[1,0,1]
	v_pk_fma_f32 v[104:105], v[8:9], v[104:105], v[108:109] op_sel_hi:[1,0,1]
	ds_read2_b32 v[108:109], v97 offset0:192 offset1:224
	v_pk_fma_f32 v[2:3], v[10:11], v[112:113], v[2:3] op_sel_hi:[1,0,1]
	ds_read2_b32 v[10:11], v96 offset0:192 offset1:224
	ds_read2_b32 v[96:97], v17 offset0:192 offset1:224
	ds_read2_b32 v[16:17], v16 offset0:192 offset1:224
	v_pk_fma_f32 v[0:1], v[8:9], v[112:113], v[0:1] op_sel_hi:[1,0,1]
	ds_read2_b32 v[8:9], v18 offset0:192 offset1:224
	s_waitcnt vmcnt(1) lgkmcnt(4)
	v_pk_fma_f32 v[6:7], v[14:15], v[108:109], v[6:7] op_sel_hi:[1,0,1]
	v_pk_fma_f32 v[4:5], v[12:13], v[108:109], v[4:5] op_sel_hi:[1,0,1]
	s_waitcnt lgkmcnt(1)
	v_pk_fma_f32 v[118:119], v[12:13], v[16:17], v[0:1] op_sel_hi:[1,0,1]
	v_mov_b32_e32 v0, v109
	v_pk_fma_f32 v[18:19], v[14:15], v[10:11], v[100:101] op_sel_hi:[1,0,1]
	v_pk_fma_f32 v[94:95], v[12:13], v[10:11], v[94:95] op_sel_hi:[1,0,1]
	s_waitcnt lgkmcnt(0)
	v_pk_fma_f32 v[98:99], v[14:15], v[8:9], v[98:99] op_sel_hi:[1,0,1]
	v_pk_fma_f32 v[100:101], v[12:13], v[8:9], v[102:103] op_sel_hi:[1,0,1]
	v_pk_fma_f32 v[102:103], v[14:15], v[96:97], v[106:107] op_sel_hi:[1,0,1]
	v_pk_fma_f32 v[104:105], v[12:13], v[96:97], v[104:105] op_sel_hi:[1,0,1]
	v_pk_fma_f32 v[106:107], v[14:15], v[16:17], v[2:3] op_sel_hi:[1,0,1]
	s_waitcnt vmcnt(0)
	v_pk_fma_f32 v[2:3], v[22:23], v[0:1], v[6:7] op_sel_hi:[1,0,1]
	v_pk_fma_f32 v[0:1], v[20:21], v[0:1], v[4:5] op_sel_hi:[1,0,1]
	v_mov_b32_e32 v4, v11
	v_mov_b32_e32 v8, v9
	v_mov_b32_e32 v12, v97
	v_mov_b32_e32 v16, v17
	v_pk_fma_f32 v[6:7], v[22:23], v[4:5], v[18:19] op_sel_hi:[1,0,1]
	v_pk_fma_f32 v[4:5], v[20:21], v[4:5], v[94:95] op_sel_hi:[1,0,1]
	v_pk_fma_f32 v[10:11], v[22:23], v[8:9], v[98:99] op_sel_hi:[1,0,1]
	v_pk_fma_f32 v[8:9], v[20:21], v[8:9], v[100:101] op_sel_hi:[1,0,1]
	v_pk_fma_f32 v[14:15], v[22:23], v[12:13], v[102:103] op_sel_hi:[1,0,1]
	v_pk_fma_f32 v[12:13], v[20:21], v[12:13], v[104:105] op_sel_hi:[1,0,1]
	v_pk_fma_f32 v[18:19], v[22:23], v[16:17], v[106:107] op_sel_hi:[1,0,1]
	v_pk_fma_f32 v[16:17], v[20:21], v[16:17], v[118:119] op_sel_hi:[1,0,1]
	ds_write_b128 v114, v[0:3] offset:20480
	ds_write_b128 v114, v[4:7] offset:20672
	ds_write_b128 v114, v[8:11] offset:20864
	ds_write_b128 v114, v[12:15] offset:21056
	ds_write_b128 v114, v[16:19] offset:21248
